# tail split guarded by grid size (applies only to the 256-workgroup grid, generic schedule otherwise); same code path as before on this chip
# baseline (speedup 1.0000x reference)
; __device__ __forceinline__ int otid() { int t = threadIdx.x; asm volatile("" : "+v"(t)); return t; }
; #define PG8_STAGE(bufoff, gbase, voff) do { _Pragma("unroll") for (int _i = 0; _i < 2; ++_i) \
;         __builtin_amdgcn_global_load_lds((const unsigned*)((const char*)(gbase) + (voff)[_i]), (PG8_LAS unsigned*)(lds + (bufoff) + ldsw + _i * 8192), 16, 0, 0); } while (0)
; #define PG8_WAIT_V(n) asm volatile("s_waitcnt vmcnt(" #n ")" ::: "memory")
; #define PG8_BAR __builtin_amdgcn_s_barrier()
; template <class Epi, class Sched, bool ALIGN_EPI = false, bool SP2 = false>
; __device__ __forceinline__ void gemm_phase(PG8_LAS unsigned char* lds, const Gemm g, const Sched& S, const Epi& E) {
;     const int tid = otid(), wid = __builtin_amdgcn_readfirstlane(tid >> 6), lane = tid & 63, wr = wid >> 2, wc = wid & 3, fr = lane & 15, fq = lane >> 4;
;     const int K = g.K, nt = K / BK;
;     unsigned voffA[2], voffB[2];
; #pragma unroll
;     for (int i = 0; i < 2; ++i) { int R, C; stage_rc(tid * 16 + i * 8192, R, C); const int Rb = Epi::PERM ? ((R & ~31) + perm32(R & 31)) : R;
;         voffA[i] = (unsigned)(R * K + C) * 2u; voffB[i] = (unsigned)(Rb * K + C) * 2u; }
;     const size_t kstep = (size_t)(BK * 2);
;     const size_t hstep = (size_t)HALF * K * 2;
;     const size_t tstep = 2 * hstep;
;     const unsigned ldsw = (unsigned)wid * 1024u;
;     const int aoff = lds_byte(wr * 64 + fr, fq * 8), boff = lds_byte(wc * 32 + fr, fq * 8);
;     ...
;     const char* cA = (const char*)g.A + (size_t)cur.pm * tstep; const char* cB = (const char*)g.Bt + (size_t)cur.pn * tstep;
;     S.a_ready(cur);
;     if constexpr (SP2) {
;         PG8_STAGE(PG8_SB(0, 0), cB, voffB); PG8_STAGE(PG8_SB(0, 1), cB + hstep, voffB); PG8_STAGE(PG8_SA(0, 0), cA, voffA); PG8_STAGE(PG8_SA(0, 1), cA + hstep, voffA);
;         if (wr == 1) PG8_BAR;
;         PG8_WAIT_V(2); PG8_BAR;
.LBB0_204:
	s_and_b64 vcc, exec, s[22:23]
	s_cbranch_vccz .LBB0_221
	v_mov_b32_e32 v11, v214
	s_cmpk_gt_i32 s49, 0x67f
	s_nop 0
	v_readfirstlane_b32 s3, v11
	s_cbranch_scc1 .LBB0_221
	s_cmp_eq_u32 s98, 0x100
	s_cselect_b32 s85, 7, -1
	s_add_i32 s84, s85, -1
	v_lshlrev_b32_e32 v0, 4, v11
	v_add_u32_e32 v2, 0x2000, v0
	s_waitcnt lgkmcnt(0)
	v_ashrrev_i32_e32 v3, 31, v2
	v_lshrrev_b32_e32 v3, 22, v3
	v_add_u32_e32 v3, v2, v3
	v_ashrrev_i32_e32 v10, 10, v3
	v_mul_i32_i24_e32 v3, 0x400, v10
	v_sub_u32_e32 v2, v2, v3
	v_lshrrev_b32_e32 v3, 4, v2
	v_bitop3_b32 v2, v3, v2, 32 bitop3:0x6c
	v_ashrrev_i32_e32 v3, 31, v2
	v_lshrrev_b32_e32 v3, 26, v3
	v_add_u32_e32 v3, v2, v3
	v_lshlrev_b32_e32 v4, 3, v10
	s_ashr_i32 s21, s20, 31
	s_mul_i32 s1, s20, 0x1a00000
	v_ashrrev_i32_e32 v12, 6, v3
	v_and_b32_e32 v4, -16, v4
	s_mul_hi_i32 s0, s20, 0x1a00000
	s_add_u32 s4, s94, s1
	v_add_u32_e32 v4, v12, v4
	s_addc_u32 s5, s95, s0
	v_and_b32_e32 v5, 3, v12
	s_mov_b32 s0, 0xfffe0
	v_lshrrev_b32_e32 v6, 2, v4
	v_lshlrev_b32_e32 v7, 1, v4
	v_and_b32_e32 v3, 0xc0, v3
	v_and_or_b32 v5, v4, s0, v5
	v_and_b32_e32 v6, 4, v6
	v_and_b32_e32 v7, 24, v7
	v_sub_u32_e32 v2, v2, v3
	v_or3_b32 v5, v5, v6, v7
	v_lshlrev_b32_e32 v6, 5, v10
	v_ashrrev_i16_sdwa v2, v207, sext(v2) dst_sel:DWORD dst_unused:UNUSED_PAD src0_sel:DWORD src1_sel:BYTE_0
	v_and_b32_e32 v6, 32, v6
	v_bfe_i32 v13, v2, 0, 16
	v_add_lshl_u32 v2, v6, v13, 1
	v_lshl_add_u32 v154, v5, 12, v2
	v_lshl_add_u32 v156, v4, 12, v2
	v_bfe_i32 v2, v11, 27, 1
	v_lshrrev_b32_e32 v2, 22, v2
	v_add_u32_e32 v2, v0, v2
	v_and_b32_e32 v2, 0xfffffc00, v2
	v_sub_u32_e32 v0, v0, v2
	v_lshrrev_b32_e32 v2, 4, v0
	v_bitop3_b32 v2, v2, v0, 32 bitop3:0x6c
	v_ashrrev_i32_e32 v0, 31, v0
	v_lshrrev_b32_e32 v0, 26, v0
	v_add_u32_e32 v0, v2, v0
	v_ashrrev_i32_e32 v14, 6, v0
	v_ashrrev_i32_e32 v0, 31, v11
	v_lshrrev_b32_e32 v0, 26, v0
	v_add_u32_e32 v0, v11, v0
	v_ashrrev_i32_e32 v15, 6, v0
	v_lshlrev_b32_e32 v0, 3, v15
	v_and_b32_e32 v0, -16, v0
	v_add_u32_e32 v3, v14, v0
	v_and_b32_e32 v0, 3, v14
	s_ashr_i32 s7, s49, 31
	v_and_or_b32 v0, v3, s0, v0
	s_lshr_b32 s0, s7, 29
	s_add_i32 s0, s49, s0
	s_ashr_i32 s13, s3, 6
	s_ashr_i32 s1, s0, 3
	s_and_b32 s0, s0, -8
	s_ashr_i32 s15, s3, 8
	s_lshl_b32 s6, s13, 10
	s_sub_i32 s0, s49, s0
	s_cmp_lt_i32 s0, 0
	s_movk_i32 s2, 0xd1
	s_cselect_b32 s2, s2, 0xd0
	s_mul_i32 s0, s0, s2
	s_add_i32 s0, s0, s1
	s_mul_hi_i32 s1, s0, 0x4ec4ec4f
	s_lshr_b32 s2, s1, 31
	s_ashr_i32 s1, s1, 5
	s_add_i32 s1, s1, s2
	s_lshl_b32 s8, s1, 2
	s_mulk_i32 s1, 0x68
	s_sub_i32 s0, s0, s1
	s_bfe_i32 s1, s0, 0x80000
	s_bfe_u32 s1, s1, 0x2000d
	s_add_i32 s1, s0, s1
	s_bfe_i32 s2, s1, 0x80000
	s_and_b32 s1, s1, 0xfc
	v_lshrrev_b32_e32 v4, 2, v3
	v_lshlrev_b32_e32 v5, 1, v3
	s_sub_i32 s0, s0, s1
	v_and_b32_e32 v4, 4, v4
	v_and_b32_e32 v5, 24, v5
	s_sext_i32_i16 s2, s2
	s_sext_i32_i8 s0, s0
	v_or3_b32 v0, v0, v4, v5
	v_mul_i32_i24_e32 v5, 64, v14
	s_lshr_b32 s2, s2, 2
	s_add_i32 s36, s8, s0
	v_sub_u32_e32 v2, v2, v5
	s_ashr_i32 s37, s36, 31
	s_bfe_i64 s[8:9], s[2:3], 0x100000
	v_lshlrev_b32_e32 v4, 5, v15
	v_ashrrev_i16_sdwa v2, v207, sext(v2) dst_sel:DWORD dst_unused:UNUSED_PAD src0_sel:DWORD src1_sel:BYTE_0
	s_lshl_b64 s[0:1], s[36:37], 20
	s_lshl_b64 s[8:9], s[8:9], 20
	v_and_b32_e32 v4, 32, v4
	v_bfe_i32 v16, v2, 0, 16
	s_add_u32 s40, s4, s8
	v_add_lshl_u32 v2, v4, v16, 1
	s_addc_u32 s41, s5, s9
	s_add_i32 s8, s6, 0
	v_lshl_add_u32 v0, v0, 12, v2
	s_add_i32 m0, s8, 0x10000
	v_lshl_add_u32 v158, v3, 12, v2
	global_load_lds_dwordx4 v0, s[40:41]
	s_add_i32 m0, s8, 0x12000
	s_add_u32 s10, s40, 0x80000
	global_load_lds_dwordx4 v154, s[40:41]
	s_addc_u32 s11, s41, 0
	s_add_i32 m0, s8, 0x14000
	v_mov_b32_e32 v155, v1
	global_load_lds_dwordx4 v0, s[10:11]
	s_add_i32 m0, s8, 0x16000
	s_add_u32 s42, s30, s0
	s_addc_u32 s43, s31, s1
	s_add_i32 s9, s8, 0x2000
	global_load_lds_dwordx4 v154, s[10:11]
	s_mov_b32 m0, s8
	s_add_u32 s0, s42, 0x80000
	global_load_lds_dwordx4 v158, s[42:43]
	s_mov_b32 m0, s9
	s_addc_u32 s1, s43, 0
	s_add_i32 s10, s8, 0x4000
	global_load_lds_dwordx4 v156, s[42:43]
	s_mov_b32 m0, s10
	s_add_i32 s11, s8, 0x6000
	global_load_lds_dwordx4 v158, s[0:1]
	s_mov_b32 m0, s11
	v_mov_b32_e32 v159, v1
	global_load_lds_dwordx4 v156, s[0:1]
	v_mov_b32_e32 v157, v1
	s_cmp_eq_u32 s15, 1
	v_lshl_add_u64 v[8:9], s[40:41], 0, v[0:1]
	v_lshl_add_u64 v[6:7], s[40:41], 0, v[154:155]
	v_lshl_add_u64 v[2:3], s[42:43], 0, v[158:159]
	s_cselect_b64 s[0:1], -1, 0
	s_cmp_lg_u32 s15, 1
	v_lshl_add_u64 v[4:5], s[42:43], 0, v[156:157]
	s_cbranch_scc1 .LBB0_208
	s_barrier

;     __host__ __device__ bool next(int i, Unit& u) const {
;         const long L = (long)i * G + c; if (L >= nwg) return false;
;         int wgid = (int)L; { const int q = nwg / NXCD, r = nwg % NXCD, xcd = wgid % NXCD, off = wgid / NXCD; wgid = (xcd < r ? xcd * (q + 1) : r * (q + 1) + (xcd - r) * q) + off; }
;         const int nig = WGM * nN, gid = wgid / nig, fm = gid * WGM, gsz = (nM - fm) < WGM ? (nM - fm) : WGM;
;         u.pm = fm + ((wgid % nig) % gsz); u.pn = (wgid % nig) / gsz; return true;
.LBB0_211:
	s_add_i32 s27, s27, 1
	s_mul_i32 s15, s27, s12
	s_mul_hi_u32 s17, s27, s98
	s_add_i32 s17, s17, s15
	s_mul_i32 s15, s27, s98
	s_add_u32 s20, s15, s49
	s_addc_u32 s21, s17, s7
	s_cmp_lg_u32 s27, s84
	s_cbranch_scc1 .Ltail_a
	s_and_b32 s20, s49, 0x7f
	s_addk_i32 s20, 0x600
	s_mov_b32 s21, 0

; template <class Epi, class Sched, bool ALIGN_EPI = false, bool SP2 = false>
; __device__ __forceinline__ void gemm_phase(PG8_LAS unsigned char* lds, const Gemm g, const Sched& S, const Epi& E) {
;     ...
;         const bool has_next = S.next(ui + 1, nxt);
;         const char* nA = has_next ? (const char*)g.A + (size_t)nxt.pm * tstep : cA; const char* nB = has_next ? (const char*)g.Bt + (size_t)nxt.pn * tstep : cB;
;     ...
; #pragma unroll
;         for (int a = 0; a < 2; ++a)
; #pragma unroll
;             for (int b = 0; b < 2; ++b)
; #pragma unroll
;                 for (int m = 0; m < 4; ++m)
; #pragma unroll
;                     for (int n = 0; n < 2; ++n) acc[a][b][m][n] = (f32x4){0.f, 0.f, 0.f, 0.f};
;         cur = nxt; cA = nA; cB = nB; ++ui;
.LBB0_213:
	s_ashr_i32 s19, s18, 31
	s_lshl_b64 s[20:21], s[18:19], 20
	s_add_u32 s20, s30, s20
	s_addc_u32 s21, s31, s21
	s_and_b64 s[22:23], s[38:39], exec
	s_cselect_b32 s15, s21, s43
	s_cselect_b32 s19, s20, s42
	s_ashr_i32 s17, s16, 31
	s_lshl_b64 s[22:23], s[16:17], 20
	s_add_u32 s22, s4, s22
	s_addc_u32 s23, s5, s23
	s_cmp_lg_u32 s27, s84
	s_cbranch_scc1 .Ltail_b
	s_lshr_b32 s34, s49, 7
	s_lshl_b32 s34, s34, 19
	s_add_u32 s22, s22, s34
	s_addc_u32 s23, s23, 0
.Ltail_b:
	s_and_b64 s[34:35], s[38:39], exec
	s_cselect_b32 s17, s23, s41
	s_cselect_b32 s37, s22, s40
	s_add_u32 s34, s42, 0x80080
	s_addc_u32 s35, s43, 0
	s_add_u32 s44, s40, 0x100
	v_mov_b32_e32 v2, 0
	s_addc_u32 s45, s41, 0
	s_mov_b32 s46, -2
	v_mov_b32_e32 v3, v2
	v_mov_b32_e32 v4, v2
	v_mov_b32_e32 v5, v2
	v_mov_b32_e32 v6, v2
	v_mov_b32_e32 v7, v2
	v_mov_b32_e32 v8, v2
	v_mov_b32_e32 v9, v2
	v_mov_b32_e32 v18, v2
	v_mov_b32_e32 v19, v2
	v_mov_b32_e32 v20, v2
	v_mov_b32_e32 v21, v2
	v_mov_b32_e32 v22, v2
	v_mov_b32_e32 v23, v2
	v_mov_b32_e32 v24, v2
	v_mov_b32_e32 v25, v2
	v_mov_b32_e32 v34, v2
	v_mov_b32_e32 v35, v2
	v_mov_b32_e32 v36, v2
	v_mov_b32_e32 v37, v2
	v_mov_b32_e32 v38, v2
	v_mov_b32_e32 v39, v2
	v_mov_b32_e32 v40, v2
	v_mov_b32_e32 v41, v2
	v_mov_b32_e32 v50, v2
	v_mov_b32_e32 v51, v2
	v_mov_b32_e32 v52, v2
	v_mov_b32_e32 v53, v2
	v_mov_b32_e32 v54, v2
	v_mov_b32_e32 v55, v2
	v_mov_b32_e32 v56, v2
	v_mov_b32_e32 v57, v2
	v_mov_b32_e32 v10, v2
	v_mov_b32_e32 v11, v2
	v_mov_b32_e32 v12, v2
	v_mov_b32_e32 v13, v2
	v_mov_b32_e32 v14, v2
	v_mov_b32_e32 v15, v2
	v_mov_b32_e32 v16, v2
	v_mov_b32_e32 v17, v2
	v_mov_b32_e32 v26, v2
	v_mov_b32_e32 v27, v2
	v_mov_b32_e32 v28, v2
	v_mov_b32_e32 v29, v2
	v_mov_b32_e32 v30, v2
	v_mov_b32_e32 v31, v2
	v_mov_b32_e32 v32, v2
	v_mov_b32_e32 v33, v2
	v_mov_b32_e32 v42, v2
	v_mov_b32_e32 v43, v2
	v_mov_b32_e32 v44, v2
	v_mov_b32_e32 v45, v2
	v_mov_b32_e32 v46, v2
	v_mov_b32_e32 v47, v2
	v_mov_b32_e32 v48, v2
	v_mov_b32_e32 v49, v2
	v_mov_b32_e32 v58, v2
	v_mov_b32_e32 v59, v2
	v_mov_b32_e32 v60, v2
	v_mov_b32_e32 v61, v2
	v_mov_b32_e32 v62, v2
	v_mov_b32_e32 v63, v2
	v_mov_b32_e32 v64, v2
	v_mov_b32_e32 v65, v2
	v_mov_b32_e32 v66, v2
	v_mov_b32_e32 v67, v2
	v_mov_b32_e32 v68, v2
	v_mov_b32_e32 v69, v2
	v_mov_b32_e32 v70, v2
	v_mov_b32_e32 v71, v2
	v_mov_b32_e32 v72, v2
	v_mov_b32_e32 v73, v2
	v_mov_b32_e32 v82, v2
	v_mov_b32_e32 v83, v2
	v_mov_b32_e32 v84, v2
	v_mov_b32_e32 v85, v2
	v_mov_b32_e32 v86, v2
	v_mov_b32_e32 v87, v2
	v_mov_b32_e32 v88, v2
	v_mov_b32_e32 v89, v2
	v_mov_b32_e32 v98, v2
	v_mov_b32_e32 v99, v2
	v_mov_b32_e32 v100, v2
	v_mov_b32_e32 v101, v2
	v_mov_b32_e32 v102, v2
	v_mov_b32_e32 v103, v2
	v_mov_b32_e32 v104, v2
	v_mov_b32_e32 v105, v2
	v_mov_b32_e32 v122, v2
	v_mov_b32_e32 v123, v2
	v_mov_b32_e32 v124, v2
	v_mov_b32_e32 v125, v2
	v_mov_b32_e32 v126, v2
	v_mov_b32_e32 v127, v2
	v_mov_b32_e32 v128, v2
	v_mov_b32_e32 v129, v2
	v_mov_b32_e32 v74, v2
	v_mov_b32_e32 v75, v2
	v_mov_b32_e32 v76, v2
	v_mov_b32_e32 v77, v2
	v_mov_b32_e32 v78, v2
	v_mov_b32_e32 v79, v2
	v_mov_b32_e32 v80, v2
	v_mov_b32_e32 v81, v2
	v_mov_b32_e32 v90, v2
	v_mov_b32_e32 v91, v2
	v_mov_b32_e32 v92, v2
	v_mov_b32_e32 v93, v2
	v_mov_b32_e32 v94, v2
	v_mov_b32_e32 v95, v2
	v_mov_b32_e32 v96, v2
	v_mov_b32_e32 v97, v2
	v_mov_b32_e32 v106, v2
	v_mov_b32_e32 v107, v2
	v_mov_b32_e32 v108, v2
	v_mov_b32_e32 v109, v2
	v_mov_b32_e32 v110, v2
	v_mov_b32_e32 v111, v2
	v_mov_b32_e32 v112, v2
	v_mov_b32_e32 v113, v2
	v_mov_b32_e32 v138, v2
	v_mov_b32_e32 v139, v2
	v_mov_b32_e32 v140, v2
	v_mov_b32_e32 v141, v2
	v_mov_b32_e32 v142, v2
	v_mov_b32_e32 v143, v2
	v_mov_b32_e32 v144, v2
	v_mov_b32_e32 v145, v2
	s_cmp_eq_u32 s27, s85
	s_cbranch_scc1 .Ltail_loop

; __device__ __forceinline__ unsigned cvt_pk_bf16(float lo, float hi) { unsigned r; asm volatile("v_cvt_pk_bf16_f32 %0, %1, %2" : "=v"(r) : "v"(lo), "v"(hi)); return r; }
;     __device__ __forceinline__ void operator()(const f32x4 (&acc)[2][2][4][2], const Unit& u, int wr, int wc, int fr, int fq) const {
;         const int row0 = u.pm * BM + wr * 64 + fr, col0 = wc * 32 + 8 * fq;
; #pragma unroll
;         for (int ai = 0; ai < 2; ++ai) {
;             f32x4 pa[4], pb[4];
; #pragma unroll
;             for (int m = 0; m < 4; ++m) { const f32x4* pp = (const f32x4*)(rowsq + (size_t)(row0 + ai * HALF + m * 16) * 32 + 8 * fq); pa[m] = pp[0]; pb[m] = pp[1]; }
; #pragma unroll
;             for (int m = 0; m < 4; ++m) { const int row = row0 + ai * HALF + m * 16; const f32x4 a = pa[m], b = pb[m];
;                 float sq = ((a[0] + a[1]) + (a[2] + a[3])) + ((b[0] + b[1]) + (b[2] + b[3])); sq += __shfl_xor(sq, 16); sq += __shfl_xor(sq, 32);
;                 const float rs = __builtin_amdgcn_rsqf(sq * inv_k + eps);
; #pragma unroll
;                 for (int bj = 0; bj < 2; ++bj) { const f32x4 v0 = acc[ai][bj][m][0] * rs, v1 = acc[ai][bj][m][1] * rs;
;                     u32x4 w; w.x = cvt_pk_bf16(v0[0], v0[1]); w.y = cvt_pk_bf16(v0[2], v0[3]); w.z = cvt_pk_bf16(v1[0], v1[1]); w.w = cvt_pk_bf16(v1[2], v1[3]);
;                     *(u32x4*)(O + ((size_t)(u.pn * 2 + bj) * Mrows + row) * HALF + col0) = w; } }
.LBB0_217:
	v_cmp_lt_i32_e32 vcc, v224, v219
	v_lshl_add_u32 v168, s36, 8, v176
	v_ashrrev_i32_e32 v169, 31, v168
	v_cndmask_b32_e32 v114, v218, v224, vcc
	v_cmp_lt_i32_e32 vcc, v225, v219
	v_lshlrev_b32_e32 v180, 2, v114
	v_or_b32_e32 v174, 16, v168
	v_cndmask_b32_e32 v114, v218, v225, vcc
	v_lshlrev_b32_e32 v179, 2, v114
	v_lshlrev_b64 v[114:115], 7, v[168:169]
	v_lshl_add_u64 v[114:115], v[162:163], 0, v[114:115]
	global_load_dwordx4 v[182:185], v[114:115], off
	global_load_dwordx4 v[186:189], v[114:115], off offset:16
	v_ashrrev_i32_e32 v175, 31, v174
	v_lshlrev_b64 v[114:115], 7, v[174:175]
	v_lshl_add_u64 v[114:115], v[162:163], 0, v[114:115]
	global_load_dwordx4 v[146:149], v[114:115], off
	global_load_dwordx4 v[150:153], v[114:115], off offset:16
	v_or_b32_e32 v172, 32, v168
	v_ashrrev_i32_e32 v173, 31, v172
	v_lshlrev_b64 v[114:115], 7, v[172:173]
	v_lshl_add_u64 v[114:115], v[162:163], 0, v[114:115]
	global_load_dwordx4 v[134:137], v[114:115], off
	global_load_dwordx4 v[130:133], v[114:115], off offset:16
	v_or_b32_e32 v170, 48, v168
	v_ashrrev_i32_e32 v171, 31, v170
	v_lshlrev_b64 v[114:115], 7, v[170:171]
	v_lshl_add_u64 v[114:115], v[162:163], 0, v[114:115]
	global_load_dwordx4 v[118:121], v[114:115], off
	s_nop 0
	global_load_dwordx4 v[114:117], v[114:115], off offset:16
	s_lshl_b32 s14, s14, 1
	s_cmp_eq_u32 s27, s85
	s_cselect_b64 s[80:81], 0, -1
	s_cbranch_scc0 .Ltail_c
	s_lshr_b32 s15, s49, 7
	s_add_i32 s14, s14, s15
